# GLA prompt recurrence rewritten: waves 0-3 keep S[256x16] in accumulators and feed it back as bf16 MFMA operand (no S^T LDS image, K-permuted q_i image), 2 barriers per chunk
# speedup vs baseline: 1.0191x; 1.0074x over previous
; __device__ __forceinline__ void gla_prompt_unit(const Args& a, unsigned char* lds, int unit, int tid) {
;     const int lane = tid & 63, wave = tid >> 6, r16 = lane & 15, q4 = lane >> 4;
;     const int bh = unit >> 3, vs = unit & 7, b = bh >> 2, h = bh & 3;
;     unsigned char* QI = lds; unsigned char* KDT = lds + 33792; unsigned char* ST = lds + 54272;
;     unsigned char* VT = lds + 88064; unsigned char* AM = lds + 93184; float* DEC = (float*)(lds + 98304);
;     const bf16_t* Z = (const bf16_t*)(a.ws + WS_Z); bf16_t* OCAT = (bf16_t*)(a.ws + WS_OCAT); float* GSS = (float*)(a.ws + WS_GSSP);
;     const bf16_t* QIg = (const bf16_t*)(a.ws + WS_QIG); const bf16_t* KDg = (const bf16_t*)(a.ws + WS_KDG); const bf16_t* AMg = (const bf16_t*)(a.ws + WS_AMG); const float* DECg = (const float*)(a.ws + WS_DECG);
;     for (int i = tid; i < 33792 / 16; i += 512) ((u32x4*)ST)[i] = (u32x4){0u, 0u, 0u, 0u};
;     f32x4 sacc[2][4];
; #pragma unroll
;     for (int i = 0; i < 2; ++i)
; #pragma unroll
;         for (int j = 0; j < 4; ++j) sacc[i][j] = (f32x4){0.f, 0.f, 0.f, 0.f};
;     const size_t rowbase = (size_t)b * 2048;
;     u32x4 rq[2], rkd[2], rv = (u32x4){0u, 0u, 0u, 0u}, ram = (u32x4){0u, 0u, 0u, 0u}, rdec = (u32x4){0u, 0u, 0u, 0u};
.LBB0_484:
	s_or_b64 exec, exec, s[0:1]
	s_cmpk_gt_i32 s33, 0xff
	s_movk_i32 s0, 0xff
	s_waitcnt lgkmcnt(0)
	s_barrier
	s_cbranch_scc1 .LBB0_521
	v_mov_b32_e32 v0, 0
	v_lshlrev_b32_e32 v70, 4, v188
	v_mov_b32_e32 v71, v0
	v_lshl_add_u64 v[6:7], s[86:87], 0, v[70:71]
	s_mov_b64 s[8:9], 0x2f100000
	v_lshl_add_u64 v[72:73], v[6:7], 0, s[8:9]
	v_lshrrev_b32_e32 v6, 2, v188
	v_mov_b32_e32 v7, 0x3fffffc0
	v_and_or_b32 v76, v6, 56, v7
	v_add_u32_e32 v7, 0xffffff00, v188
	v_cmp_lt_u32_e64 s[8:9], s0, v188
	s_movk_i32 s0, 0x100
	v_lshrrev_b32_e32 v7, 2, v7
	v_cmp_gt_u32_e64 s[10:11], s0, v188
	v_and_b32_e32 v78, 0x3ffffff8, v7
	v_and_b32_e32 v7, 0x1f0, v70
	s_add_i32 s0, 0, 0x16c00
	v_add_u32_e32 v11, 0, v7
	s_movk_i32 s3, 0x50
	v_mov_b32_e32 v7, s0
	s_add_i32 s0, 0, 0x18000
	v_mul_u32_u24_e32 v13, 0x50, v6
	v_mad_u32_u24 v77, v6, s3, v7
	v_add_u32_e32 v6, s0, v70
	v_add_u32_e32 v79, 0xfffff800, v6
	v_bfe_u32 v6, v188, 6, 2
	v_lshlrev_b32_e32 v2, 1, v91
	v_mov_b32_e32 v3, v0
	v_lshlrev_b32_e32 v8, 4, v6
	v_lshl_add_u64 v[4:5], s[86:87], 0, v[2:3]
	v_and_b32_e32 v74, 31, v188
	s_add_i32 s14, 0, 0x15800
	v_or_b32_e32 v14, v8, v124
	s_movk_i32 s15, 0x210
	v_and_b32_e32 v16, 48, v188
	v_and_or_b32 v80, v126, 48, v124
	v_mov_b32_e32 v27, 0x4200
	v_lshl_add_u64 v[82:83], s[76:77], 0, v[2:3]
	v_add_u32_e32 v2, 0, v70
	v_mov_b32_e32 v10, s14
	v_lshl_add_u32 v81, v74, 1, s14
	v_mad_u32_u24 v15, v14, s15, 0
	v_mad_u32_u24 v17, v80, s15, 0
	v_add_u32_e32 v21, s14, v16
	v_mad_u32_u24 v27, v124, s15, v27
	s_mov_b64 s[14:15], 0x2cd00000
	v_add_u32_e32 v123, 0xd400, v2
	s_movk_i32 s40, 0x5e00
	v_mov_b64_e32 v[2:3], 0xc6bdc00
	v_and_b32_e32 v19, 48, v186
	v_mul_u32_u24_e32 v22, 0x210, v87
	v_mul_u32_u24_e32 v23, 0x210, v84
	v_lshl_add_u64 v[84:85], v[4:5], 0, s[14:15]
	v_mad_u64_u32 v[86:87], s[14:15], v74, s40, v[2:3]
	v_lshrrev_b32_e32 v1, 4, v186
	s_mov_b64 s[6:7], 0x2ed00000
	v_mad_u32_u24 v18, v80, s3, v7
	v_lshlrev_b32_e32 v7, 5, v148
	v_add3_u32 v114, s0, v19, v125
	s_mov_b64 s[14:15], 0x2ed00800
	v_lshlrev_b32_e32 v2, 9, v80
	v_lshlrev_b32_e32 v3, 2, v6
	s_mov_b32 s0, 0x33700000
	v_lshl_add_u64 v[68:69], v[4:5], 0, s[6:7]
	v_mad_u32_u24 v14, v14, s3, v10
	v_lshlrev_b32_e32 v10, 2, v1
	v_lshrrev_b32_e32 v24, 2, v89
	v_or_b32_e32 v19, v7, v124
	v_lshl_add_u64 v[88:89], v[70:71], 0, s[14:15]
	s_mov_b64 s[14:15], 0x2f0ffc00
	v_or3_b32 v92, v2, v3, s0
	v_mul_u32_u24_e32 v2, 0x1800, v80
	v_lshlrev_b32_e32 v4, 5, v6
	v_lshrrev_b32_e32 v5, 1, v16
	s_movk_i32 s1, 0x80
	v_and_b32_e32 v9, 0x3c0, v188
	v_and_b32_e32 v75, 48, v70
	v_mul_u32_u24_e32 v26, 0x50, v19
	v_or_b32_e32 v19, 16, v19
	v_lshlrev_b32_e32 v1, 3, v1
	v_or_b32_e32 v7, v10, v7
	v_lshl_add_u64 v[90:91], v[70:71], 0, s[14:15]
	v_mul_hi_u32_u24_e32 v3, 0x1800, v80
	v_or3_b32 v2, v2, v4, v5
	s_mov_b64 s[14:15], 0x24a00800
	v_cmp_eq_u32_e64 s[6:7], s1, v9
	v_add_u32_e32 v12, 0, v75
	v_add_u32_e32 v20, 0, v16
	v_mul_u32_u24_e32 v24, 0x50, v24
	v_mul_u32_u24_e32 v25, 0x50, v124
	v_mul_u32_u24_e32 v19, 0x50, v19
	v_add3_u32 v1, 0, v9, v1
	v_mul_u32_u24_e32 v9, 0x210, v124
	s_add_u32 s38, s84, 0x8600000
	v_lshlrev_b32_e32 v115, 9, v7
	v_lshl_add_u64 v[94:95], v[2:3], 0, s[14:15]
	v_mbcnt_lo_u32_b32 v2, -1, 0
	v_readlane_b32 s52, v249, 33
	v_cmp_gt_u32_e64 s[4:5], s1, v188
	s_mov_b32 s1, 0
	v_cmp_gt_u32_e64 s[12:13], 16, v186
	s_addc_u32 s39, s85, 0
	v_or_b32_e32 v116, 0x200, v115
	v_or_b32_e32 v117, 0x400, v115
	v_or_b32_e32 v118, 0x600, v115
	v_or_b32_e32 v119, 0x2000, v115
	v_or_b32_e32 v120, 0x2200, v115
	v_or_b32_e32 v121, 0x2400, v115
	v_or_b32_e32 v122, 0x2600, v115
	v_add_u32_e32 v125, 0xfffffe00, v188
	v_mov_b32_e32 v93, v0
	s_movk_i32 s41, 0x1800
	s_movk_i32 s42, 0x63f
	s_mov_b64 s[14:15], 0xbc000
	s_mov_b64 s[16:17], 0x800
	s_mov_b64 s[18:19], 0x400
	s_mov_b64 s[20:21], 0x4000
	s_mov_b64 s[22:23], 0x30000
	s_mov_b64 s[24:25], 0x7e0
	v_lshlrev_b32_e32 v96, 1, v8
	v_lshlrev_b32_e32 v98, 1, v10
	s_mov_b32 s43, 0x24a00000
	v_lshlrev_b32_e32 v100, 2, v6
	v_mov_b32_e32 v4, 0
	v_mov_b32_e32 v5, v0
	v_mov_b32_e32 v6, v0
	v_mov_b32_e32 v7, v0
	v_mov_b32_e32 v71, 0x5e00
	v_add_u32_e32 v126, v11, v22
	v_add_u32_e32 v127, v12, v13
	v_add_u32_e32 v128, v11, v23
	v_add_u32_e32 v129, v12, v24
	v_add_u32_e32 v130, v15, v16
	v_add_u32_e32 v131, v17, v16
	v_add_u32_e32 v132, v14, v16
	v_add_u32_e32 v133, v18, v16
	v_mbcnt_hi_u32_b32 v134, -1, v2
	v_add_u32_e32 v135, v20, v26
	v_add_u32_e32 v136, v21, v25
	v_add_u32_e32 v137, v20, v19
	v_add_u32_e32 v138, v1, v9
	v_add_u32_e32 v139, v1, v27
	s_mov_b32 s44, s33
	v_readlane_b32 s53, v249, 34
	s_branch .LBB0_487
.LBB0_487:
	s_mov_b64 s[26:27], 0
	v_mov_b32_e32 v1, v125
	v_mov_b32_e32 v2, v123

; __device__ __forceinline__ void gla_prompt_unit(const Args& a, unsigned char* lds, int unit, int tid) {
;     ...
;     f32x4 sacc[2][4];
; #pragma unroll
;     for (int i = 0; i < 2; ++i)
; #pragma unroll
;         for (int j = 0; j < 4; ++j) sacc[i][j] = (f32x4){0.f, 0.f, 0.f, 0.f};
;     const size_t rowbase = (size_t)b * 2048;
;     u32x4 rq[2], rkd[2], rv = (u32x4){0u, 0u, 0u, 0u}, ram = (u32x4){0u, 0u, 0u, 0u}, rdec = (u32x4){0u, 0u, 0u, 0u};
;     ...
;     GLA_LOAD(0);
;     for (int n = 0; n < 64; ++n) {
;         const size_t row0 = rowbase + (size_t)n * 32;
; #pragma unroll
;         for (int i = 0; i < 2; ++i) { const int ch = tid + i * 512; *(u32x4*)(QI + (ch >> 5) * 528 + (ch & 31) * 16) = rq[i]; *(u32x4*)(KDT + (ch >> 2) * 80 + (ch & 3) * 16) = rkd[i]; }
.LBB0_497:
	s_or_b64 exec, exec, s[26:27]
	s_lshl_b32 s50, s33, 7
	s_mul_i32 s48, s36, 0x2f00000
	s_and_b32 s50, s50, 0xc00
	s_and_b32 s0, s44, 7
	s_mul_hi_i32 s49, s36, 0x2f00000
	s_or_b32 s48, s48, s50
	v_or_b32_e32 v108, s34, v70
	s_lshl_b32 s34, s33, 4
	s_lshl_b64 s[26:27], s[30:31], 19
	s_lshl_b32 s0, s0, 4
	v_lshl_add_u64 v[2:3], s[48:49], 0, v[86:87]
	s_lshl_b64 s[48:49], s[30:31], 17
	s_lshl_b64 s[30:31], s[30:31], 16
	s_and_b32 s34, s34, 0x180
	v_lshl_add_u64 v[106:107], v[90:91], 0, s[30:31]
	s_lshl_b64 s[30:31], s[36:37], 20
	s_or_b32 s0, s0, s34
	v_lshlrev_b64 v[10:11], 1, v[102:103]
	s_or_b32 s30, s30, s0
	s_mul_i32 s0, s36, 0xc00000
	v_mul_lo_u32 v1, v9, s3
	v_lshl_add_u64 v[2:3], v[2:3], 0, v[10:11]
	v_lshlrev_b32_e32 v8, 1, v8
	v_mov_b32_e32 v9, v0
	v_lshl_add_u64 v[110:111], s[30:31], 0, v[92:93]
	s_mul_hi_i32 s31, s36, 0xc00000
	s_or_b32 s30, s0, s50
	v_lshl_add_u64 v[2:3], v[2:3], 0, v[8:9]
	v_lshl_add_u64 v[8:9], s[30:31], 0, v[94:95]
	v_lshl_add_u64 v[112:113], v[8:9], 0, v[10:11]
	v_mov_b32_e32 v8, 0
	v_lshl_add_u64 v[104:105], v[88:89], 0, s[48:49]
	v_mov_b32_e32 v109, s35
	s_mov_b32 s0, 63
	v_mov_b32_e32 v9, v8
	v_mov_b32_e32 v10, v8
	v_mov_b32_e32 v11, v8
	v_mov_b32_e32 v12, v8
	v_mov_b32_e32 v13, v8
	v_mov_b32_e32 v14, v8
	v_mov_b32_e32 v15, v8
	v_mov_b32_e32 v16, v8
	v_mov_b32_e32 v17, v8
	v_mov_b32_e32 v18, v8
	v_mov_b32_e32 v19, v8
	v_mov_b32_e32 v20, v8
	v_mov_b32_e32 v21, v8
	v_mov_b32_e32 v22, v8
	v_mov_b32_e32 v23, v8
	v_mov_b32_e32 v24, v8
	v_mov_b32_e32 v25, v8
	v_mov_b32_e32 v26, v8
	v_mov_b32_e32 v27, v8
	v_mov_b32_e32 v28, v8
	v_mov_b32_e32 v29, v8
	v_mov_b32_e32 v30, v8
	v_mov_b32_e32 v31, v8
	v_mov_b32_e32 v32, v8
	v_mov_b32_e32 v33, v8
	v_mov_b32_e32 v34, v8
	v_mov_b32_e32 v35, v8
	v_mov_b32_e32 v36, v8
	v_mov_b32_e32 v37, v8
	v_mov_b32_e32 v38, v8
	v_mov_b32_e32 v39, v8
	v_and_b32_e32 v97, 15, v186
	v_lshrrev_b32_e32 v99, 4, v186
	v_mul_u32_u24_e32 v222, 0x210, v97
	v_lshl_add_u32 v222, v99, 4, v222
	v_mul_u32_u24_e32 v101, 0x50, v97
	v_lshl_add_u32 v101, v99, 4, v101
	v_add_u32_e32 v223, 0x16c00, v101
	v_add_u32_e32 v225, 0x8400, v101
	v_mul_u32_u24_e32 v141, 0x500, v148
	v_add_u32_e32 v224, v141, v101
	v_add_u32_e32 v224, 0x15800, v224
	v_lshlrev_b32_e32 v226, 4, v99
	v_add_u32_e32 v226, 0x18000, v226
	v_xor_b32_e32 v227, 16, v186
	v_lshlrev_b32_e32 v227, 2, v227
	v_xor_b32_e32 v228, 32, v186
	v_lshlrev_b32_e32 v228, 2, v228
	v_and_b32_e32 v141, 1, v188
	v_lshlrev_b32_e32 v141, 4, v141
	v_bfe_u32 v229, v188, 1, 1
	v_mul_u32_u24_e32 v229, 24, v229
	v_sub_u32_e32 v141, v141, v229
	v_add_u32_e32 v230, v126, v141
	v_add_u32_e32 v234, v128, v141
	v_readfirstlane_b32 s96, v148
	s_mov_b64 s[98:99], 0x18000
	s_mov_b64 s[92:93], 0x2000
	v_mov_b32_e32 v190, 0
	v_mov_b32_e32 v191, 0
	v_mov_b32_e32 v192, 0
	v_mov_b32_e32 v193, 0
	v_mov_b32_e32 v194, 0
	v_mov_b32_e32 v195, 0
	v_mov_b32_e32 v196, 0
	v_mov_b32_e32 v197, 0
	v_mov_b32_e32 v198, 0
	v_mov_b32_e32 v199, 0
	v_mov_b32_e32 v200, 0
	v_mov_b32_e32 v201, 0
	v_mov_b32_e32 v202, 0
	v_mov_b32_e32 v203, 0
	v_mov_b32_e32 v204, 0
	v_mov_b32_e32 v205, 0
	v_mov_b32_e32 v206, 0
	v_mov_b32_e32 v207, 0
	v_mov_b32_e32 v208, 0
	v_mov_b32_e32 v209, 0
	v_mov_b32_e32 v210, 0
	v_mov_b32_e32 v211, 0
	v_mov_b32_e32 v212, 0
	v_mov_b32_e32 v213, 0
	v_mov_b32_e32 v214, 0
	v_mov_b32_e32 v215, 0
	v_mov_b32_e32 v216, 0
	v_mov_b32_e32 v217, 0
	v_mov_b32_e32 v218, 0
	v_mov_b32_e32 v219, 0
	v_mov_b32_e32 v220, 0
	v_mov_b32_e32 v221, 0
.Lgn_loop:
.Lgn_a499:
	s_waitcnt vmcnt(3)
	ds_write2_b64 v230, v[48:49], v[50:51] offset1:2
	s_waitcnt vmcnt(2)
	ds_write_b128 v127, v[52:55] offset:33792
	s_waitcnt vmcnt(1)
	ds_write2_b64 v234, v[56:57], v[58:59] offset1:2
	s_waitcnt vmcnt(0)
	ds_write_b128 v129, v[60:63] offset:33792
	s_and_saveexec_b64 s[30:31], s[4:5]
	s_cbranch_execnz .Lgn_a509
	s_or_b64 exec, exec, s[30:31]
	s_and_saveexec_b64 s[30:31], s[6:7]
	s_cbranch_execnz .Lgn_a510

; __device__ __forceinline__ void gla_prompt_unit(const Args& a, unsigned char* lds, int unit, int tid) {
;     ...
;         if (n + 1 < 64) GLA_LOAD(n + 1);
.Lgn_a503:
	s_or_b64 exec, exec, s[30:31]
	s_cmp_eq_u32 s0, 0
	s_cbranch_scc1 .Lgn_a507
	v_lshl_add_u64 v[56:57], s[86:87], 0, v[108:109]
	v_add_co_u32_e32 v48, vcc, 0x2ad04000, v56
	s_nop 1
	v_addc_co_u32_e32 v49, vcc, 0, v57, vcc
	v_add_co_u32_e32 v52, vcc, 0x2cd04000, v56
	s_nop 1
	v_addc_co_u32_e32 v53, vcc, 0, v57, vcc
	v_add_co_u32_e32 v58, vcc, 0x2ad06000, v56
	global_load_dwordx4 v[48:51], v[48:49], off
	s_nop 0
	global_load_dwordx4 v[52:55], v[52:53], off
	v_addc_co_u32_e32 v59, vcc, 0, v57, vcc
	v_add_co_u32_e32 v60, vcc, 0x2cd06000, v56
	s_nop 1
	v_addc_co_u32_e32 v61, vcc, 0, v57, vcc
	global_load_dwordx4 v[56:59], v[58:59], off
	s_nop 0
	global_load_dwordx4 v[60:63], v[60:61], off
	s_and_saveexec_b64 s[30:31], s[4:5]
	s_cbranch_execnz .Lgn_a511
	s_or_b64 exec, exec, s[30:31]
	s_and_saveexec_b64 s[30:31], s[6:7]
	s_cbranch_execnz .Lgn_a512

; __device__ __forceinline__ unsigned cvt_pk_bf16(float lo, float hi) { unsigned r; asm volatile("v_cvt_pk_bf16_f32 %0, %1, %2" : "=v"(r) : "v"(lo), "v"(hi)); return r; }
; #define MFMA_SETTLE1(a) asm volatile("s_nop 15\n\ts_nop 15" : "+v"(a))
; #define LBAR() asm volatile("s_waitcnt lgkmcnt(0)\n\ts_barrier" ::: "memory")
; __device__ __forceinline__ void gla_prompt_unit(const Args& a, unsigned char* lds, int unit, int tid) {
;     ...
;         const int vt = wave & 3, lt = wave >> 2;
;         f32x4 oacc = (f32x4){0.f, 0.f, 0.f, 0.f};
; #pragma unroll
;         for (int kk = 0; kk < 8; ++kk) { const bf16x8 af = *(const bf16x8*)(ST + (vt * 16 + r16) * 528 + kk * 64 + q4 * 16); const bf16x8 bfg = *(const bf16x8*)(QI + (lt * 16 + r16) * 528 + kk * 64 + q4 * 16);
;             oacc = __builtin_amdgcn_mfma_f32_16x16x32_bf16(af, bfg, oacc, 0, 0, 0); }
;         { const bf16x8 af = *(const bf16x8*)(VT + (vt * 16 + r16) * 80 + q4 * 16); const bf16x8 bfg = *(const bf16x8*)(AM + (lt * 16 + r16) * 80 + q4 * 16);
;           oacc = __builtin_amdgcn_mfma_f32_16x16x32_bf16(af, bfg, oacc, 0, 0, 0);
;           MFMA_SETTLE1(oacc);
;           const size_t row = row0 + lt * 16 + r16;
;           *(u32x2*)(OCAT + row * OC + 1024 + h * 512 + vs * 64 + vt * 16 + q4 * 4) = (u32x2){cvt_pk_bf16(oacc[0], oacc[1]), cvt_pk_bf16(oacc[2], oacc[3])};
;           float ss = (oacc[0] * oacc[0] + oacc[1] * oacc[1]) + (oacc[2] * oacc[2] + oacc[3] * oacc[3]); ss += __shfl_xor(ss, 16); ss += __shfl_xor(ss, 32);
;           if (lane < 16) GSS[(row * 4 + h) * 32 + vs * 4 + vt] = ss; }
;         LBAR();
; #pragma unroll
;         for (int k2 = 0; k2 < 2; ++k2) { const int kt = wave * 2 + k2; const f32x4 dec4 = *(const f32x4*)(DEC + kt * 16 + q4 * 4); const bf16x8 af = *(const bf16x8*)(KDT + (kt * 16 + r16) * 80 + q4 * 16);
; #pragma unroll
;             for (int v2 = 0; v2 < 4; ++v2) { const bf16x8 bfg = *(const bf16x8*)(VT + (v2 * 16 + r16) * 80 + q4 * 16);
;                 sacc[k2][v2] = __builtin_amdgcn_mfma_f32_16x16x32_bf16(af, bfg, sacc[k2][v2] * dec4, 0, 0, 0); } }
.Lgn_a507:
	s_or_b64 exec, exec, s[30:31]
	s_waitcnt lgkmcnt(0)
	s_barrier
	s_cmp_gt_u32 s96, 3
	s_cbranch_scc1 .Lgn_skip
	ds_read_b128 v[178:181], v224
	ds_read_b128 v[162:165], v222
	ds_read_b128 v[166:169], v222 offset:8448
	ds_read_b128 v[170:173], v222 offset:64
	ds_read_b128 v[174:177], v222 offset:8512
	ds_read_b128 v[236:239], v222 offset:128
	ds_read_b128 v[240:243], v222 offset:8576
	ds_read_b128 v[244:247], v222 offset:192
	ds_read_b128 v[250:253], v222 offset:8640
	v_cvt_pk_bf16_f32 v150, v8, v9
	v_cvt_pk_bf16_f32 v151, v10, v11
	v_cvt_pk_bf16_f32 v152, v12, v13
	v_cvt_pk_bf16_f32 v153, v14, v15
	s_waitcnt lgkmcnt(6)
	s_nop 0
	v_mfma_f32_16x16x32_bf16 v[142:145], v[150:153], v[162:165], 0
	v_mfma_f32_16x16x32_bf16 v[158:161], v[150:153], v[166:169], 0
	ds_read_b128 v[162:165], v222 offset:256
	ds_read_b128 v[166:169], v222 offset:8704
	v_cvt_pk_bf16_f32 v154, v16, v17
	v_cvt_pk_bf16_f32 v155, v18, v19
	v_cvt_pk_bf16_f32 v156, v20, v21
	v_cvt_pk_bf16_f32 v157, v22, v23
	s_waitcnt lgkmcnt(6)
	s_nop 0
	v_mfma_f32_16x16x32_bf16 v[142:145], v[154:157], v[170:173], v[142:145]
	v_mfma_f32_16x16x32_bf16 v[158:161], v[154:157], v[174:177], v[158:161]
	ds_read_b128 v[170:173], v222 offset:320
	ds_read_b128 v[174:177], v222 offset:8768
	v_cvt_pk_bf16_f32 v150, v24, v25
	v_cvt_pk_bf16_f32 v151, v26, v27
	v_cvt_pk_bf16_f32 v152, v28, v29
	v_cvt_pk_bf16_f32 v153, v30, v31
	s_waitcnt lgkmcnt(6)
	s_nop 0
	v_mfma_f32_16x16x32_bf16 v[142:145], v[150:153], v[236:239], v[142:145]
	v_mfma_f32_16x16x32_bf16 v[158:161], v[150:153], v[240:243], v[158:161]
	ds_read_b128 v[236:239], v222 offset:384
	ds_read_b128 v[240:243], v222 offset:8832
	v_cvt_pk_bf16_f32 v154, v32, v33
	v_cvt_pk_bf16_f32 v155, v34, v35
	v_cvt_pk_bf16_f32 v156, v36, v37
	v_cvt_pk_bf16_f32 v157, v38, v39
	s_waitcnt lgkmcnt(6)
	s_nop 0
	v_mfma_f32_16x16x32_bf16 v[142:145], v[154:157], v[244:247], v[142:145]
	v_mfma_f32_16x16x32_bf16 v[158:161], v[154:157], v[250:253], v[158:161]
	ds_read_b128 v[244:247], v222 offset:448
	ds_read_b128 v[250:253], v222 offset:8896
	v_cvt_pk_bf16_f32 v150, v190, v191
	v_cvt_pk_bf16_f32 v151, v192, v193
	v_cvt_pk_bf16_f32 v152, v194, v195
	v_cvt_pk_bf16_f32 v153, v196, v197
	s_waitcnt lgkmcnt(6)
	s_nop 0
	v_mfma_f32_16x16x32_bf16 v[142:145], v[150:153], v[162:165], v[142:145]
	v_mfma_f32_16x16x32_bf16 v[158:161], v[150:153], v[166:169], v[158:161]
	ds_read_b128 v[162:165], v223
	ds_read_b128 v[166:169], v223 offset:1280
	v_cvt_pk_bf16_f32 v154, v198, v199
	v_cvt_pk_bf16_f32 v155, v200, v201
	v_cvt_pk_bf16_f32 v156, v202, v203
	v_cvt_pk_bf16_f32 v157, v204, v205
	s_waitcnt lgkmcnt(6)
	s_nop 0
	v_mfma_f32_16x16x32_bf16 v[142:145], v[154:157], v[170:173], v[142:145]
	v_mfma_f32_16x16x32_bf16 v[158:161], v[154:157], v[174:177], v[158:161]
	v_cvt_pk_bf16_f32 v150, v206, v207
	v_cvt_pk_bf16_f32 v151, v208, v209
	v_cvt_pk_bf16_f32 v152, v210, v211
	v_cvt_pk_bf16_f32 v153, v212, v213
	s_waitcnt lgkmcnt(4)
	s_nop 0
	v_mfma_f32_16x16x32_bf16 v[142:145], v[150:153], v[236:239], v[142:145]
	v_mfma_f32_16x16x32_bf16 v[158:161], v[150:153], v[240:243], v[158:161]
	v_cvt_pk_bf16_f32 v154, v214, v215
	v_cvt_pk_bf16_f32 v155, v216, v217
	v_cvt_pk_bf16_f32 v156, v218, v219
	v_cvt_pk_bf16_f32 v157, v220, v221
	s_waitcnt lgkmcnt(2)
	s_nop 0
	v_mfma_f32_16x16x32_bf16 v[142:145], v[154:157], v[244:247], v[142:145]
	v_mfma_f32_16x16x32_bf16 v[158:161], v[154:157], v[250:253], v[158:161]
	s_waitcnt lgkmcnt(0)
	v_mfma_f32_16x16x32_bf16 v[142:145], v[178:181], v[162:165], v[142:145]
	v_mfma_f32_16x16x32_bf16 v[158:161], v[178:181], v[166:169], v[158:161]
	ds_read_b128 v[170:173], v225
	ds_read_b128 v[174:177], v226
	ds_read_b128 v[236:239], v225 offset:1280
	ds_read_b128 v[240:243], v226 offset:64
	ds_read_b128 v[244:247], v225 offset:2560
	ds_read_b128 v[250:253], v226 offset:128
	ds_read_b128 v[162:165], v225 offset:3840
	ds_read_b128 v[166:169], v226 offset:192
	s_waitcnt lgkmcnt(6)
	v_pk_mul_f32 v[8:9], v[8:9], v[174:175]
	v_pk_mul_f32 v[10:11], v[10:11], v[176:177]
	s_nop 1
	v_mfma_f32_16x16x32_bf16 v[8:11], v[170:173], v[178:181], v[8:11]
	ds_read_b128 v[170:173], v225 offset:5120
	ds_read_b128 v[174:177], v226 offset:256
	s_waitcnt lgkmcnt(6)
	v_pk_mul_f32 v[12:13], v[12:13], v[240:241]
	v_pk_mul_f32 v[14:15], v[14:15], v[242:243]
	s_nop 1
	v_mfma_f32_16x16x32_bf16 v[12:15], v[236:239], v[178:181], v[12:15]
	ds_read_b128 v[236:239], v225 offset:6400
	ds_read_b128 v[240:243], v226 offset:320
	s_waitcnt lgkmcnt(6)
	v_pk_mul_f32 v[16:17], v[16:17], v[250:251]
	v_pk_mul_f32 v[18:19], v[18:19], v[252:253]
	s_nop 1
	v_mfma_f32_16x16x32_bf16 v[16:19], v[244:247], v[178:181], v[16:19]
	ds_read_b128 v[244:247], v225 offset:7680
	ds_read_b128 v[250:253], v226 offset:384
	s_waitcnt lgkmcnt(6)
; __device__ __forceinline__ unsigned cvt_pk_bf16(float lo, float hi) { unsigned r; asm volatile("v_cvt_pk_bf16_f32 %0, %1, %2" : "=v"(r) : "v"(lo), "v"(hi)); return r; }
; #define MFMA_SETTLE8(a, b, c, d, e, f, g, h) asm volatile("s_nop 15\n\ts_nop 15" : "+v"(a), "+v"(b), "+v"(c), "+v"(d), "+v"(e), "+v"(f), "+v"(g), "+v"(h))
; #define LBAR() asm volatile("s_waitcnt lgkmcnt(0)\n\ts_barrier" ::: "memory")
; __device__ __forceinline__ void gla_prompt_unit(const Args& a, unsigned char* lds, int unit, int tid) {
;     ...
;           const size_t row = row0 + lt * 16 + r16;
;           *(u32x2*)(OCAT + row * OC + 1024 + h * 512 + vs * 64 + vt * 16 + q4 * 4) = (u32x2){cvt_pk_bf16(oacc[0], oacc[1]), cvt_pk_bf16(oacc[2], oacc[3])};
;           float ss = (oacc[0] * oacc[0] + oacc[1] * oacc[1]) + (oacc[2] * oacc[2] + oacc[3] * oacc[3]); ss += __shfl_xor(ss, 16); ss += __shfl_xor(ss, 32);
;           if (lane < 16) GSS[(row * 4 + h) * 32 + vs * 4 + vt] = ss; }
;         LBAR();
; #pragma unroll
;         for (int k2 = 0; k2 < 2; ++k2) { const int kt = wave * 2 + k2; const f32x4 dec4 = *(const f32x4*)(DEC + kt * 16 + q4 * 4); const bf16x8 af = *(const bf16x8*)(KDT + (kt * 16 + r16) * 80 + q4 * 16);
; #pragma unroll
;             for (int v2 = 0; v2 < 4; ++v2) { const bf16x8 bfg = *(const bf16x8*)(VT + (v2 * 16 + r16) * 80 + q4 * 16);
;                 sacc[k2][v2] = __builtin_amdgcn_mfma_f32_16x16x32_bf16(af, bfg, sacc[k2][v2] * dec4, 0, 0, 0); } }
;         MFMA_SETTLE8(sacc[0][0], sacc[0][1], sacc[0][2], sacc[0][3], sacc[1][0], sacc[1][1], sacc[1][2], sacc[1][3]);
; #pragma unroll
;         for (int k2 = 0; k2 < 2; ++k2) { const int kt = wave * 2 + k2;
; #pragma unroll
;             for (int v2 = 0; v2 < 4; ++v2)
;                 *(u32x2*)(ST + (v2 * 16 + r16) * 528 + (kt * 16 + q4 * 4) * 2) = (u32x2){cvt_pk_bf16(sacc[k2][v2][0], sacc[k2][v2][1]), cvt_pk_bf16(sacc[k2][v2][2], sacc[k2][v2][3])}; }
;         LBAR();
	v_pk_mul_f32 v[20:21], v[20:21], v[166:167]
	v_pk_mul_f32 v[22:23], v[22:23], v[168:169]
	s_nop 1
	v_mfma_f32_16x16x32_bf16 v[20:23], v[162:165], v[178:181], v[20:23]
	ds_read_b128 v[162:165], v225 offset:8960
	ds_read_b128 v[166:169], v226 offset:448
	s_waitcnt lgkmcnt(6)
	v_pk_mul_f32 v[24:25], v[24:25], v[174:175]
	v_pk_mul_f32 v[26:27], v[26:27], v[176:177]
	s_nop 1
	v_mfma_f32_16x16x32_bf16 v[24:27], v[170:173], v[178:181], v[24:27]
	ds_read_b128 v[170:173], v225 offset:10240
	ds_read_b128 v[174:177], v226 offset:512
	s_waitcnt lgkmcnt(6)
	v_pk_mul_f32 v[28:29], v[28:29], v[240:241]
	v_pk_mul_f32 v[30:31], v[30:31], v[242:243]
	s_nop 1
	v_mfma_f32_16x16x32_bf16 v[28:31], v[236:239], v[178:181], v[28:31]
	ds_read_b128 v[236:239], v225 offset:11520
	ds_read_b128 v[240:243], v226 offset:576
	s_waitcnt lgkmcnt(6)
	v_pk_mul_f32 v[32:33], v[32:33], v[250:251]
	v_pk_mul_f32 v[34:35], v[34:35], v[252:253]
	s_nop 1
	v_mfma_f32_16x16x32_bf16 v[32:35], v[244:247], v[178:181], v[32:35]
	ds_read_b128 v[244:247], v225 offset:12800
	ds_read_b128 v[250:253], v226 offset:640
	s_waitcnt lgkmcnt(6)
	v_pk_mul_f32 v[36:37], v[36:37], v[166:167]
	v_pk_mul_f32 v[38:39], v[38:39], v[168:169]
	s_nop 1
	v_mfma_f32_16x16x32_bf16 v[36:39], v[162:165], v[178:181], v[36:39]
	ds_read_b128 v[162:165], v225 offset:14080
	ds_read_b128 v[166:169], v226 offset:704
	s_waitcnt lgkmcnt(6)
	v_pk_mul_f32 v[190:191], v[190:191], v[174:175]
	v_pk_mul_f32 v[192:193], v[192:193], v[176:177]
	s_nop 1
	v_mfma_f32_16x16x32_bf16 v[190:193], v[170:173], v[178:181], v[190:193]
	ds_read_b128 v[170:173], v225 offset:15360
	ds_read_b128 v[174:177], v226 offset:768
	s_waitcnt lgkmcnt(6)
	v_pk_mul_f32 v[194:195], v[194:195], v[240:241]
	v_pk_mul_f32 v[196:197], v[196:197], v[242:243]
	s_nop 1
	v_mfma_f32_16x16x32_bf16 v[194:197], v[236:239], v[178:181], v[194:197]
	ds_read_b128 v[236:239], v225 offset:16640
	ds_read_b128 v[240:243], v226 offset:832
	s_waitcnt lgkmcnt(6)
	v_pk_mul_f32 v[198:199], v[198:199], v[250:251]
	v_pk_mul_f32 v[200:201], v[200:201], v[252:253]
	s_nop 1
	v_mfma_f32_16x16x32_bf16 v[198:201], v[244:247], v[178:181], v[198:201]
	ds_read_b128 v[244:247], v225 offset:17920
	ds_read_b128 v[250:253], v226 offset:896
	s_waitcnt lgkmcnt(6)
	v_pk_mul_f32 v[202:203], v[202:203], v[166:167]
	v_pk_mul_f32 v[204:205], v[204:205], v[168:169]
	s_nop 1
	v_mfma_f32_16x16x32_bf16 v[202:205], v[162:165], v[178:181], v[202:205]
	ds_read_b128 v[162:165], v225 offset:19200
	ds_read_b128 v[166:169], v226 offset:960
	s_waitcnt lgkmcnt(6)
	v_pk_mul_f32 v[206:207], v[206:207], v[174:175]
	v_pk_mul_f32 v[208:209], v[208:209], v[176:177]
	s_nop 1
	v_mfma_f32_16x16x32_bf16 v[206:209], v[170:173], v[178:181], v[206:209]
	s_waitcnt lgkmcnt(4)
	v_pk_mul_f32 v[210:211], v[210:211], v[240:241]
	v_pk_mul_f32 v[212:213], v[212:213], v[242:243]
	s_nop 1
	v_mfma_f32_16x16x32_bf16 v[210:213], v[236:239], v[178:181], v[210:213]
	s_waitcnt lgkmcnt(2)
	v_pk_mul_f32 v[214:215], v[214:215], v[250:251]
	v_pk_mul_f32 v[216:217], v[216:217], v[252:253]
	s_nop 1
	v_mfma_f32_16x16x32_bf16 v[214:217], v[244:247], v[178:181], v[214:217]
	s_waitcnt lgkmcnt(0)
	v_pk_mul_f32 v[218:219], v[218:219], v[166:167]
	v_pk_mul_f32 v[220:221], v[220:221], v[168:169]
	s_nop 1
	v_mfma_f32_16x16x32_bf16 v[218:221], v[162:165], v[178:181], v[218:221]
	v_mul_f32_e32 v150, v143, v143
	v_mul_f32_e32 v151, v145, v145
	v_fmac_f32_e32 v150, v142, v142
	v_fmac_f32_e32 v151, v144, v144
	v_add_f32_e32 v150, v150, v151
	ds_bpermute_b32 v151, v227, v150
	v_mul_f32_e32 v152, v159, v159
	v_mul_f32_e32 v153, v161, v161
	v_fmac_f32_e32 v152, v158, v158
	v_fmac_f32_e32 v153, v160, v160
	v_add_f32_e32 v152, v152, v153
	ds_bpermute_b32 v153, v227, v152
	v_lshl_add_u64 v[162:163], s[86:87], 0, v[112:113]
	v_lshl_add_u64 v[164:165], v[162:163], 0, s[98:99]
	v_cvt_pk_bf16_f32 v170, v142, v143
	v_cvt_pk_bf16_f32 v171, v144, v145
	v_cvt_pk_bf16_f32 v172, v158, v159
	v_cvt_pk_bf16_f32 v173, v160, v161
	global_store_dwordx2 v[162:163], v[170:171], off
	global_store_dwordx2 v[164:165], v[172:173], off
	s_waitcnt lgkmcnt(0)
	v_add_f32_e32 v150, v150, v151
	v_add_f32_e32 v152, v152, v153
	ds_bpermute_b32 v151, v228, v150
	ds_bpermute_b32 v153, v228, v152
	v_lshl_add_u64 v[166:167], s[86:87], 0, v[110:111]
	v_lshl_add_u64 v[168:169], v[166:167], 0, s[92:93]
	s_waitcnt lgkmcnt(0)
	v_add_f32_e32 v150, v150, v151
	v_add_f32_e32 v152, v152, v153
	s_and_saveexec_b64 s[30:31], s[12:13]
	global_store_dword v[166:167], v150, off
	global_store_dword v[168:169], v152, off
	s_or_b64 exec, exec, s[30:31]
.Lgn_skip:
	v_lshl_add_u64 v[2:3], v[2:3], 0, s[14:15]
	v_lshl_add_u64 v[104:105], v[104:105], 0, s[16:17]
	v_lshl_add_u64 v[106:107], v[106:107], 0, s[18:19]
	v_lshl_add_u64 v[108:109], v[108:109], 0, s[20:21]
	v_lshl_add_u64 v[110:111], v[110:111], 0, s[20:21]
	v_lshl_add_u64 v[112:113], v[112:113], 0, s[22:23]
	s_waitcnt lgkmcnt(0)
	s_barrier
	s_add_i32 s0, s0, -1
	s_cmp_ge_i32 s0, 0
	s_cbranch_scc1 .Lgn_loop
	s_branch .Lgn_fin

; __device__ __forceinline__ void gla_prompt_unit(const Args& a, unsigned char* lds, int unit, int tid) {
;     ...
;     float* SP = a.out + OUT_SP + (size_t)bh * 256 * 512;
; #pragma unroll
;     for (int k2 = 0; k2 < 2; ++k2)
; #pragma unroll
;         for (int v2 = 0; v2 < 4; ++v2)
; #pragma unroll
;             for (int j = 0; j < 4; ++j) SP[(size_t)((wave * 2 + k2) * 16 + q4 * 4 + j) * 512 + vs * 64 + v2 * 16 + r16] = sacc[k2][v2][j];
;     __syncthreads();
.Lgn_fin:
	s_cmp_gt_u32 s96, 3
	s_cbranch_scc1 .Lgn_tail
	s_ashr_i32 s54, s33, 3
	s_lshl_b32 s54, s54, 19
	s_and_b32 s55, s33, 7
	s_lshl_b32 s55, s55, 8
	s_add_i32 s54, s54, s55
	s_add_u32 s54, s38, s54
	s_addc_u32 s55, s39, 0
	s_mov_b64 s[58:59], 0x8000
	s_mov_b64 s[60:61], 0x1000
	v_lshlrev_b32_e32 v232, 13, v99
	v_lshl_add_u32 v232, v148, 6, v232
	v_lshl_add_u32 v232, v97, 2, v232
	v_mov_b32_e32 v233, 0
	v_lshl_add_u64 v[236:237], s[54:55], 0, v[232:233]
	v_lshl_add_u64 v[238:239], v[236:237], 0, s[60:61]
	global_store_dword v[236:237], v8, off
	global_store_dword v[236:237], v9, off offset:2048
	global_store_dword v[238:239], v10, off
	global_store_dword v[238:239], v11, off offset:2048
	v_lshl_add_u64 v[236:237], v[236:237], 0, s[58:59]
	v_lshl_add_u64 v[238:239], v[238:239], 0, s[58:59]
	global_store_dword v[236:237], v12, off
	global_store_dword v[236:237], v13, off offset:2048
	global_store_dword v[238:239], v14, off
	global_store_dword v[238:239], v15, off offset:2048
	v_lshl_add_u64 v[236:237], v[236:237], 0, s[58:59]
	v_lshl_add_u64 v[238:239], v[238:239], 0, s[58:59]
	global_store_dword v[236:237], v16, off
	global_store_dword v[236:237], v17, off offset:2048
	global_store_dword v[238:239], v18, off
	global_store_dword v[238:239], v19, off offset:2048
	v_lshl_add_u64 v[236:237], v[236:237], 0, s[58:59]
	v_lshl_add_u64 v[238:239], v[238:239], 0, s[58:59]
	global_store_dword v[236:237], v20, off
	global_store_dword v[236:237], v21, off offset:2048
	global_store_dword v[238:239], v22, off
	global_store_dword v[238:239], v23, off offset:2048
	v_lshl_add_u64 v[236:237], v[236:237], 0, s[58:59]
	v_lshl_add_u64 v[238:239], v[238:239], 0, s[58:59]
	global_store_dword v[236:237], v24, off
	global_store_dword v[236:237], v25, off offset:2048
	global_store_dword v[238:239], v26, off
	global_store_dword v[238:239], v27, off offset:2048
	v_lshl_add_u64 v[236:237], v[236:237], 0, s[58:59]
	v_lshl_add_u64 v[238:239], v[238:239], 0, s[58:59]
	global_store_dword v[236:237], v28, off
	global_store_dword v[236:237], v29, off offset:2048
	global_store_dword v[238:239], v30, off
	global_store_dword v[238:239], v31, off offset:2048
	v_lshl_add_u64 v[236:237], v[236:237], 0, s[58:59]
	v_lshl_add_u64 v[238:239], v[238:239], 0, s[58:59]
	global_store_dword v[236:237], v32, off
	global_store_dword v[236:237], v33, off offset:2048
	global_store_dword v[238:239], v34, off
	global_store_dword v[238:239], v35, off offset:2048
	v_lshl_add_u64 v[236:237], v[236:237], 0, s[58:59]
	v_lshl_add_u64 v[238:239], v[238:239], 0, s[58:59]
	global_store_dword v[236:237], v36, off
	global_store_dword v[236:237], v37, off offset:2048
	global_store_dword v[238:239], v38, off
	global_store_dword v[238:239], v39, off offset:2048
	v_lshl_add_u64 v[236:237], v[236:237], 0, s[58:59]
	v_lshl_add_u64 v[238:239], v[238:239], 0, s[58:59]
	global_store_dword v[236:237], v190, off
	global_store_dword v[236:237], v191, off offset:2048
	global_store_dword v[238:239], v192, off
	global_store_dword v[238:239], v193, off offset:2048
	v_lshl_add_u64 v[236:237], v[236:237], 0, s[58:59]
	v_lshl_add_u64 v[238:239], v[238:239], 0, s[58:59]
	global_store_dword v[236:237], v194, off
	global_store_dword v[236:237], v195, off offset:2048
	global_store_dword v[238:239], v196, off
	global_store_dword v[238:239], v197, off offset:2048
	v_lshl_add_u64 v[236:237], v[236:237], 0, s[58:59]
	v_lshl_add_u64 v[238:239], v[238:239], 0, s[58:59]
	global_store_dword v[236:237], v198, off
	global_store_dword v[236:237], v199, off offset:2048
	global_store_dword v[238:239], v200, off
	global_store_dword v[238:239], v201, off offset:2048
	v_lshl_add_u64 v[236:237], v[236:237], 0, s[58:59]
	v_lshl_add_u64 v[238:239], v[238:239], 0, s[58:59]
	global_store_dword v[236:237], v202, off
	global_store_dword v[236:237], v203, off offset:2048
	global_store_dword v[238:239], v204, off
	global_store_dword v[238:239], v205, off offset:2048
	v_lshl_add_u64 v[236:237], v[236:237], 0, s[58:59]
	v_lshl_add_u64 v[238:239], v[238:239], 0, s[58:59]
	global_store_dword v[236:237], v206, off
	global_store_dword v[236:237], v207, off offset:2048
	global_store_dword v[238:239], v208, off
	global_store_dword v[238:239], v209, off offset:2048
	v_lshl_add_u64 v[236:237], v[236:237], 0, s[58:59]
	v_lshl_add_u64 v[238:239], v[238:239], 0, s[58:59]
	global_store_dword v[236:237], v210, off
	global_store_dword v[236:237], v211, off offset:2048
	global_store_dword v[238:239], v212, off
	global_store_dword v[238:239], v213, off offset:2048
	v_lshl_add_u64 v[236:237], v[236:237], 0, s[58:59]
	v_lshl_add_u64 v[238:239], v[238:239], 0, s[58:59]
	global_store_dword v[236:237], v214, off
	global_store_dword v[236:237], v215, off offset:2048
	global_store_dword v[238:239], v216, off
	global_store_dword v[238:239], v217, off offset:2048
	v_lshl_add_u64 v[236:237], v[236:237], 0, s[58:59]
	v_lshl_add_u64 v[238:239], v[238:239], 0, s[58:59]
	global_store_dword v[236:237], v218, off
	global_store_dword v[236:237], v219, off offset:2048
	global_store_dword v[238:239], v220, off
	global_store_dword v[238:239], v221, off offset:2048
.Lgn_tail:
	v_readlane_b32 s26, v249, 21
	s_add_i32 s33, s33, s26
	s_add_i32 s44, s44, s26
	s_cmpk_lt_i32 s33, 0x100
	s_waitcnt lgkmcnt(0)
	s_barrier
	v_readlane_b32 s27, v249, 22
	s_cbranch_scc0 .LBB0_521
	s_branch .LBB0_487

; __global__ void __launch_bounds__(512, 2) hybrid_fwd(Args a) {
;     extern __shared__ __attribute__((aligned(16))) unsigned char lds[];
	.amdhsa_kernel _Z10hybrid_fwd4Args
		.amdhsa_group_segment_fixed_size 0
		.amdhsa_private_segment_fixed_size 0
		.amdhsa_kernarg_size 424
		.amdhsa_user_sgpr_count 2
		.amdhsa_user_sgpr_dispatch_ptr 0
		.amdhsa_user_sgpr_queue_ptr 0
		.amdhsa_user_sgpr_kernarg_segment_ptr 1
		.amdhsa_user_sgpr_dispatch_id 0
		.amdhsa_user_sgpr_kernarg_preload_length 0
		.amdhsa_user_sgpr_kernarg_preload_offset 0
		.amdhsa_user_sgpr_private_segment_size 0
		.amdhsa_uses_dynamic_stack 0
		.amdhsa_enable_private_segment 0
		.amdhsa_system_sgpr_workgroup_id_x 1
		.amdhsa_system_sgpr_workgroup_id_y 0
		.amdhsa_system_sgpr_workgroup_id_z 0
		.amdhsa_system_sgpr_workgroup_info 0
		.amdhsa_system_vgpr_workitem_id 2
		.amdhsa_next_free_vgpr 256
		.amdhsa_next_free_sgpr 102
		.amdhsa_accum_offset 256
		.amdhsa_reserve_vcc 1
		.amdhsa_float_round_mode_32 0
		.amdhsa_float_round_mode_16_64 0
		.amdhsa_float_denorm_mode_32 3
		.amdhsa_float_denorm_mode_16_64 3
		.amdhsa_dx10_clamp 1
		.amdhsa_ieee_mode 1
		.amdhsa_fp16_overflow 0
		.amdhsa_tg_split 0
		.amdhsa_exception_fp_ieee_invalid_op 0
		.amdhsa_exception_fp_denorm_src 0
		.amdhsa_exception_fp_ieee_div_zero 0
		.amdhsa_exception_fp_ieee_overflow 0
		.amdhsa_exception_fp_ieee_underflow 0
		.amdhsa_exception_fp_ieee_inexact 0
		.amdhsa_exception_int_div_zero 0
	.end_amdhsa_kernel

amdhsa.kernels:
  - .agpr_count:     0
    .args:
      - .offset:         0
        .size:           168
        .value_kind:     by_value
      - .offset:         168
        .size:           4
        .value_kind:     hidden_block_count_x
      - .offset:         172
        .size:           4
        .value_kind:     hidden_block_count_y
      - .offset:         176
        .size:           4
        .value_kind:     hidden_block_count_z
      - .offset:         180
        .size:           2
        .value_kind:     hidden_group_size_x
      - .offset:         182
        .size:           2
        .value_kind:     hidden_group_size_y
      - .offset:         184
        .size:           2
        .value_kind:     hidden_group_size_z
      - .offset:         186
        .size:           2
        .value_kind:     hidden_remainder_x
      - .offset:         188
        .size:           2
        .value_kind:     hidden_remainder_y
      - .offset:         190
        .size:           2
        .value_kind:     hidden_remainder_z
      - .offset:         208
        .size:           8
        .value_kind:     hidden_global_offset_x
      - .offset:         216
        .size:           8
        .value_kind:     hidden_global_offset_y
      - .offset:         224
        .size:           8
        .value_kind:     hidden_global_offset_z
      - .offset:         232
        .size:           2
        .value_kind:     hidden_grid_dims
      - .offset:         256
        .size:           8
        .value_kind:     hidden_multigrid_sync_arg
      - .offset:         288
        .size:           4
        .value_kind:     hidden_dynamic_lds_size
    .group_segment_fixed_size: 0
    .kernarg_segment_align: 8
    .kernarg_segment_size: 424
    .language:       OpenCL C
    .language_version:
      - 2
      - 0
    .max_flat_workgroup_size: 512
    .name:           _Z10hybrid_fwd4Args
    .private_segment_fixed_size: 0
    .sgpr_count:     108
    .sgpr_spill_count: 43
    .symbol:         _Z10hybrid_fwd4Args.kd
    .uniform_work_group_size: 1
    .uses_dynamic_stack: false
    .vgpr_count:     256
    .vgpr_spill_count: 0
    .wavefront_size: 64
